# v8 + K-loop MFMA pairs n-outer with m snake (3,2,1,0 on the second weight fragment)
# baseline (speedup 1.0000x reference)
; #define PG8_STAGE(bufoff, gbase, voff) do { _Pragma("unroll") for (int _i = 0; _i < 2; ++_i) \
;         __builtin_amdgcn_global_load_lds((const unsigned*)((const char*)(gbase) + (voff)[_i]), (PG8_LAS unsigned*)(lds + (bufoff) + ldsw + _i * 8192), 16, 0, 0); } while (0)
; #define PG8_LDA(dst, b, h) do { _Pragma("unroll") for (int m = 0; m < 4; ++m) _Pragma("unroll") for (int k = 0; k < 2; ++k) dst[m][k] = *(const PG8_LAS bf16x8*)(lds + PG8_SA(b, h) + aoff + m * 2048 + k * 1024); } while (0)
; #define PG8_LDB(dst, b, h) do { _Pragma("unroll") for (int n = 0; n < 2; ++n) _Pragma("unroll") for (int k = 0; k < 2; ++k) dst[n][k] = *(const PG8_LAS bf16x8*)(lds + PG8_SB(b, h) + boff + n * 2048 + k * 1024); } while (0)
; #define PG8_MMA(ai, bj, At, Bt) do { __builtin_amdgcn_s_setprio(1); _Pragma("unroll") for (int m = 0; m < 4; ++m) _Pragma("unroll") for (int n = 0; n < 2; ++n) _Pragma("unroll") for (int k = 0; k < 2; ++k) \
;         acc[ai][bj][m][n] = __builtin_amdgcn_mfma_f32_16x16x32_bf16(Bt[n][k], At[m][k], acc[ai][bj][m][n], 0, 0, 0); __builtin_amdgcn_s_setprio(0); } while (0)
; #define PG8_WAIT_V(n) asm volatile("s_waitcnt vmcnt(" #n ")" ::: "memory")
; #define PG8_WAIT_L(n) asm volatile("s_waitcnt lgkmcnt(" #n ")" ::: "memory")
; #define PG8_BAR __builtin_amdgcn_s_barrier()
; #define PG8_SCHED __builtin_amdgcn_sched_barrier(0)
; template <class Epi, class Sched, bool ALIGN_EPI = false, bool SP2 = false>
; __device__ __forceinline__ void gemm_phase(PG8_LAS unsigned char* lds, const Gemm g, const Sched& S, const Epi& E, const int tid) {
;     ...
;             PG8_LDB(B0, 0, 0); PG8_LDB(B1, 0, 1); PG8_SCHED; PG8_LDA(At, 0, 0); PG8_STAGE(PG8_SA(1, 1), a1 + hstep, voffA);
;             PG8_WAIT_V(8); PG8_WAIT_L(0); PG8_BAR; PG8_MMA(0, 0, At, B0); PG8_MMA(0, 1, At, B1); PG8_BAR; PG8_SCHED;
;             PG8_LDA(At, 0, 1); PG8_STAGE(PG8_SB(0, 0), b2, voffB); PG8_STAGE(PG8_SB(0, 1), b2 + hstep, voffB); PG8_STAGE(PG8_SA(0, 0), a2, voffA);
;             PG8_WAIT_V(8); PG8_WAIT_L(0); PG8_BAR; PG8_MMA(1, 0, At, B0); PG8_MMA(1, 1, At, B1); PG8_BAR; PG8_SCHED;
.LBB0_209:
	s_add_i32 s69, s10, 2
	s_add_u32 s74, s0, 0x80
	s_addc_u32 s11, s1, 0
	s_add_i32 s81, 0, 0x10000
	s_cmp_eq_u32 s39, s10
	s_cselect_b32 s11, s31, s11
	s_cselect_b32 s10, s30, s74
	s_cselect_b32 s77, s35, s13
	s_cselect_b32 s76, s34, s12
	s_add_i32 s74, 0, 0x14000
	v_add_u32_e32 v142, s81, v180
	v_add_u32_e32 v168, s74, v180
	s_waitcnt lgkmcnt(0)
	ds_read_b128 v[130:133], v142
	ds_read_b128 v[134:137], v142 offset:1024
	ds_read_b128 v[138:141], v142 offset:2048
	ds_read_b128 v[142:145], v142 offset:3072
	ds_read_b128 v[164:167], v168
	ds_read_b128 v[184:187], v168 offset:1024
	ds_read_b128 v[188:191], v168 offset:2048
	ds_read_b128 v[200:203], v168 offset:3072
	v_lshl_add_u64 v[168:169], s[0:1], 0, v[160:161]
	s_add_i32 m0, s78, 0xc000
	ds_read_b128 v[204:207], v181
	ds_read_b128 v[208:211], v181 offset:1024
	ds_read_b128 v[212:215], v181 offset:2048
	ds_read_b128 v[216:219], v181 offset:3072
	ds_read_b128 v[220:223], v181 offset:4096
	ds_read_b128 v[226:229], v181 offset:5120
	ds_read_b128 v[238:241], v181 offset:6144
	ds_read_b128 v[242:245], v181 offset:7168
	global_load_lds_dwordx4 v[168:169], off
	v_lshl_add_u64 v[168:169], s[0:1], 0, v[162:163]
	s_add_i32 m0, s78, 0xe000
	s_nop 0
	global_load_lds_dwordx4 v[168:169], off
	s_waitcnt vmcnt(8)
	s_waitcnt lgkmcnt(0)
	s_barrier
	s_setprio 1
	s_waitcnt lgkmcnt(0)
	v_mfma_f32_16x16x32_bf16 v[126:129], v[130:133], v[204:207], v[126:129]
	v_mfma_f32_16x16x32_bf16 v[126:129], v[134:137], v[208:211], v[126:129]
	v_mfma_f32_16x16x32_bf16 v[110:113], v[130:133], v[212:215], v[110:113]
	v_mfma_f32_16x16x32_bf16 v[110:113], v[134:137], v[216:219], v[110:113]
	v_mfma_f32_16x16x32_bf16 v[94:97], v[130:133], v[220:223], v[94:97]
	v_mfma_f32_16x16x32_bf16 v[94:97], v[134:137], v[226:229], v[94:97]
	v_mfma_f32_16x16x32_bf16 v[78:81], v[130:133], v[238:241], v[78:81]
	v_mfma_f32_16x16x32_bf16 v[78:81], v[134:137], v[242:245], v[78:81]
	v_mfma_f32_16x16x32_bf16 v[74:77], v[138:141], v[238:241], v[74:77]
	v_mfma_f32_16x16x32_bf16 v[74:77], v[142:145], v[242:245], v[74:77]
	v_mfma_f32_16x16x32_bf16 v[90:93], v[138:141], v[220:223], v[90:93]
	v_mfma_f32_16x16x32_bf16 v[90:93], v[142:145], v[226:229], v[90:93]
	v_mfma_f32_16x16x32_bf16 v[106:109], v[138:141], v[212:215], v[106:109]
	v_mfma_f32_16x16x32_bf16 v[106:109], v[142:145], v[216:219], v[106:109]
	v_mfma_f32_16x16x32_bf16 v[122:125], v[138:141], v[204:207], v[122:125]
	v_mfma_f32_16x16x32_bf16 v[122:125], v[142:145], v[208:211], v[122:125]
	s_setprio 0
	s_setprio 1
	v_mfma_f32_16x16x32_bf16 v[118:121], v[164:167], v[204:207], v[118:121]
	v_mfma_f32_16x16x32_bf16 v[118:121], v[184:187], v[208:211], v[118:121]
	v_mfma_f32_16x16x32_bf16 v[102:105], v[164:167], v[212:215], v[102:105]
	v_mfma_f32_16x16x32_bf16 v[102:105], v[184:187], v[216:219], v[102:105]
	v_mfma_f32_16x16x32_bf16 v[86:89], v[164:167], v[220:223], v[86:89]
	v_mfma_f32_16x16x32_bf16 v[86:89], v[184:187], v[226:229], v[86:89]
	v_mfma_f32_16x16x32_bf16 v[70:73], v[164:167], v[238:241], v[70:73]
	v_mfma_f32_16x16x32_bf16 v[70:73], v[184:187], v[242:245], v[70:73]
	v_mfma_f32_16x16x32_bf16 v[66:69], v[188:191], v[238:241], v[66:69]
	v_mfma_f32_16x16x32_bf16 v[66:69], v[200:203], v[242:245], v[66:69]
	v_mfma_f32_16x16x32_bf16 v[82:85], v[188:191], v[220:223], v[82:85]
	v_mfma_f32_16x16x32_bf16 v[82:85], v[200:203], v[226:229], v[82:85]
	v_mfma_f32_16x16x32_bf16 v[98:101], v[188:191], v[212:215], v[98:101]
	v_mfma_f32_16x16x32_bf16 v[98:101], v[200:203], v[216:219], v[98:101]
	v_mfma_f32_16x16x32_bf16 v[114:117], v[188:191], v[204:207], v[114:117]
	v_mfma_f32_16x16x32_bf16 v[114:117], v[200:203], v[208:211], v[114:117]
	s_setprio 0
	s_barrier
	s_add_i32 s81, s81, s75
	v_lshl_add_u64 v[168:169], s[76:77], 0, v[148:149]
	s_mov_b32 m0, s81
	ds_read_b128 v[204:207], v181 offset:16384
	ds_read_b128 v[208:211], v181 offset:17408
	ds_read_b128 v[212:215], v181 offset:18432
	ds_read_b128 v[216:219], v181 offset:19456
	ds_read_b128 v[220:223], v181 offset:20480
	ds_read_b128 v[226:229], v181 offset:21504
	ds_read_b128 v[238:241], v181 offset:22528
	ds_read_b128 v[242:245], v181 offset:23552
	global_load_lds_dwordx4 v[168:169], off
	s_add_i32 m0, s81, 0x2000
	v_lshl_add_u64 v[246:247], s[76:77], 0, v[152:153]
	s_add_u32 s76, s76, s82
	s_addc_u32 s77, s77, 0
	s_add_i32 s74, s74, s75
	global_load_lds_dwordx4 v[246:247], off
	v_lshl_add_u64 v[248:249], s[76:77], 0, v[148:149]
	s_mov_b32 m0, s74
	v_lshl_add_u64 v[250:251], s[76:77], 0, v[152:153]
	global_load_lds_dwordx4 v[248:249], off
	s_add_i32 m0, s74, 0x2000
	v_lshl_add_u64 v[252:253], s[10:11], 0, v[146:147]
	global_load_lds_dwordx4 v[250:251], off
	s_mov_b32 m0, s78
	v_lshl_add_u64 v[194:195], s[10:11], 0, v[150:151]
	global_load_lds_dwordx4 v[252:253], off
	s_mov_b32 m0, s79
	s_nop 0
	global_load_lds_dwordx4 v[194:195], off
	s_waitcnt vmcnt(8)
	s_waitcnt lgkmcnt(0)
	s_barrier
; #define PG8_STAGE(bufoff, gbase, voff) do { _Pragma("unroll") for (int _i = 0; _i < 2; ++_i) \
;         __builtin_amdgcn_global_load_lds((const unsigned*)((const char*)(gbase) + (voff)[_i]), (PG8_LAS unsigned*)(lds + (bufoff) + ldsw + _i * 8192), 16, 0, 0); } while (0)
; #define PG8_LDA(dst, b, h) do { _Pragma("unroll") for (int m = 0; m < 4; ++m) _Pragma("unroll") for (int k = 0; k < 2; ++k) dst[m][k] = *(const PG8_LAS bf16x8*)(lds + PG8_SA(b, h) + aoff + m * 2048 + k * 1024); } while (0)
; #define PG8_LDB(dst, b, h) do { _Pragma("unroll") for (int n = 0; n < 2; ++n) _Pragma("unroll") for (int k = 0; k < 2; ++k) dst[n][k] = *(const PG8_LAS bf16x8*)(lds + PG8_SB(b, h) + boff + n * 2048 + k * 1024); } while (0)
; #define PG8_MMA(ai, bj, At, Bt) do { __builtin_amdgcn_s_setprio(1); _Pragma("unroll") for (int m = 0; m < 4; ++m) _Pragma("unroll") for (int n = 0; n < 2; ++n) _Pragma("unroll") for (int k = 0; k < 2; ++k) \
;         acc[ai][bj][m][n] = __builtin_amdgcn_mfma_f32_16x16x32_bf16(Bt[n][k], At[m][k], acc[ai][bj][m][n], 0, 0, 0); __builtin_amdgcn_s_setprio(0); } while (0)
; #define PG8_WAIT_V(n) asm volatile("s_waitcnt vmcnt(" #n ")" ::: "memory")
; #define PG8_WAIT_L(n) asm volatile("s_waitcnt lgkmcnt(" #n ")" ::: "memory")
; #define PG8_BAR __builtin_amdgcn_s_barrier()
; #define PG8_SCHED __builtin_amdgcn_sched_barrier(0)
; template <class Epi, class Sched, bool ALIGN_EPI = false, bool SP2 = false>
; __device__ __forceinline__ void gemm_phase(PG8_LAS unsigned char* lds, const Gemm g, const Sched& S, const Epi& E, const int tid) {
;     ...
;             PG8_WAIT_V(8); PG8_WAIT_L(0); PG8_BAR; PG8_MMA(1, 0, At, B0); PG8_MMA(1, 1, At, B1); PG8_BAR; PG8_SCHED;
;             PG8_LDB(B0, 1, 0); PG8_LDB(B1, 1, 1); PG8_SCHED; PG8_LDA(At, 1, 0); PG8_STAGE(PG8_SA(0, 1), a2 + hstep, voffA);
;             PG8_WAIT_V(8); PG8_WAIT_L(0); PG8_BAR; PG8_MMA(0, 0, At, B0); PG8_MMA(0, 1, At, B1); PG8_BAR; PG8_SCHED;
	s_setprio 1
	s_waitcnt lgkmcnt(0)
	v_mfma_f32_16x16x32_bf16 v[62:65], v[130:133], v[204:207], v[62:65]
	v_mfma_f32_16x16x32_bf16 v[62:65], v[134:137], v[208:211], v[62:65]
	v_mfma_f32_16x16x32_bf16 v[46:49], v[130:133], v[212:215], v[46:49]
	v_mfma_f32_16x16x32_bf16 v[46:49], v[134:137], v[216:219], v[46:49]
	v_mfma_f32_16x16x32_bf16 v[30:33], v[130:133], v[220:223], v[30:33]
	v_mfma_f32_16x16x32_bf16 v[30:33], v[134:137], v[226:229], v[30:33]
	v_mfma_f32_16x16x32_bf16 v[14:17], v[130:133], v[238:241], v[14:17]
	v_mfma_f32_16x16x32_bf16 v[14:17], v[134:137], v[242:245], v[14:17]
	v_mfma_f32_16x16x32_bf16 v[10:13], v[138:141], v[238:241], v[10:13]
	v_mfma_f32_16x16x32_bf16 v[10:13], v[142:145], v[242:245], v[10:13]
	v_mfma_f32_16x16x32_bf16 v[26:29], v[138:141], v[220:223], v[26:29]
	v_mfma_f32_16x16x32_bf16 v[26:29], v[142:145], v[226:229], v[26:29]
	v_mfma_f32_16x16x32_bf16 v[42:45], v[138:141], v[212:215], v[42:45]
	v_mfma_f32_16x16x32_bf16 v[42:45], v[142:145], v[216:219], v[42:45]
	v_mfma_f32_16x16x32_bf16 v[58:61], v[138:141], v[204:207], v[58:61]
	v_mfma_f32_16x16x32_bf16 v[58:61], v[142:145], v[208:211], v[58:61]
	s_setprio 0
	s_setprio 1
	v_mfma_f32_16x16x32_bf16 v[54:57], v[164:167], v[204:207], v[54:57]
	v_mfma_f32_16x16x32_bf16 v[54:57], v[184:187], v[208:211], v[54:57]
	v_mfma_f32_16x16x32_bf16 v[38:41], v[164:167], v[212:215], v[38:41]
	v_mfma_f32_16x16x32_bf16 v[38:41], v[184:187], v[216:219], v[38:41]
	v_mfma_f32_16x16x32_bf16 v[22:25], v[164:167], v[220:223], v[22:25]
	v_mfma_f32_16x16x32_bf16 v[22:25], v[184:187], v[226:229], v[22:25]
	v_mfma_f32_16x16x32_bf16 v[6:9], v[164:167], v[238:241], v[6:9]
	v_mfma_f32_16x16x32_bf16 v[6:9], v[184:187], v[242:245], v[6:9]
	v_mfma_f32_16x16x32_bf16 v[2:5], v[188:191], v[238:241], v[2:5]
	v_mfma_f32_16x16x32_bf16 v[2:5], v[200:203], v[242:245], v[2:5]
	v_mfma_f32_16x16x32_bf16 v[18:21], v[188:191], v[220:223], v[18:21]
	v_mfma_f32_16x16x32_bf16 v[18:21], v[200:203], v[226:229], v[18:21]
	v_mfma_f32_16x16x32_bf16 v[34:37], v[188:191], v[212:215], v[34:37]
	v_mfma_f32_16x16x32_bf16 v[34:37], v[200:203], v[216:219], v[34:37]
	v_mfma_f32_16x16x32_bf16 v[50:53], v[188:191], v[204:207], v[50:53]
	v_mfma_f32_16x16x32_bf16 v[50:53], v[200:203], v[208:211], v[50:53]
	s_setprio 0
	s_barrier
	s_add_i32 s74, 0, 0x18000
	s_add_i32 s76, 0, 0x1c000
	v_add_u32_e32 v142, s74, v180
	v_add_u32_e32 v183, s76, v180
	ds_read_b128 v[130:133], v142
	ds_read_b128 v[134:137], v142 offset:1024
	ds_read_b128 v[138:141], v142 offset:2048
	ds_read_b128 v[142:145], v142 offset:3072
	ds_read_b128 v[164:167], v183
	ds_read_b128 v[184:187], v183 offset:1024
	ds_read_b128 v[188:191], v183 offset:2048
	ds_read_b128 v[200:203], v183 offset:3072
	s_add_u32 s10, s10, s82
	s_addc_u32 s11, s11, 0
	s_mov_b32 m0, s36
	v_lshl_add_u64 v[198:199], s[10:11], 0, v[146:147]
	ds_read_b128 v[204:207], v181 offset:32768
	ds_read_b128 v[208:211], v181 offset:33792
	ds_read_b128 v[212:215], v181 offset:34816
	ds_read_b128 v[216:219], v181 offset:35840
	ds_read_b128 v[220:223], v181 offset:36864
	ds_read_b128 v[226:229], v181 offset:37888
	ds_read_b128 v[238:241], v181 offset:38912
	ds_read_b128 v[242:245], v181 offset:39936
	global_load_lds_dwordx4 v[198:199], off
	v_lshl_add_u64 v[198:199], s[10:11], 0, v[150:151]
	s_mov_b32 m0, s37
	s_nop 0
	global_load_lds_dwordx4 v[198:199], off
	s_waitcnt vmcnt(8)
	s_waitcnt lgkmcnt(0)
	s_barrier
	s_setprio 1
	s_waitcnt lgkmcnt(0)
	v_mfma_f32_16x16x32_bf16 v[126:129], v[130:133], v[204:207], v[126:129]
	v_mfma_f32_16x16x32_bf16 v[126:129], v[134:137], v[208:211], v[126:129]
	v_mfma_f32_16x16x32_bf16 v[110:113], v[130:133], v[212:215], v[110:113]
	v_mfma_f32_16x16x32_bf16 v[110:113], v[134:137], v[216:219], v[110:113]
	v_mfma_f32_16x16x32_bf16 v[94:97], v[130:133], v[220:223], v[94:97]
	v_mfma_f32_16x16x32_bf16 v[94:97], v[134:137], v[226:229], v[94:97]
	v_mfma_f32_16x16x32_bf16 v[78:81], v[130:133], v[238:241], v[78:81]
	v_mfma_f32_16x16x32_bf16 v[78:81], v[134:137], v[242:245], v[78:81]
	v_mfma_f32_16x16x32_bf16 v[74:77], v[138:141], v[238:241], v[74:77]
	v_mfma_f32_16x16x32_bf16 v[74:77], v[142:145], v[242:245], v[74:77]
	v_mfma_f32_16x16x32_bf16 v[90:93], v[138:141], v[220:223], v[90:93]
	v_mfma_f32_16x16x32_bf16 v[90:93], v[142:145], v[226:229], v[90:93]
	v_mfma_f32_16x16x32_bf16 v[106:109], v[138:141], v[212:215], v[106:109]
	v_mfma_f32_16x16x32_bf16 v[106:109], v[142:145], v[216:219], v[106:109]
	v_mfma_f32_16x16x32_bf16 v[122:125], v[138:141], v[204:207], v[122:125]
	v_mfma_f32_16x16x32_bf16 v[122:125], v[142:145], v[208:211], v[122:125]
	s_setprio 0
	s_setprio 1
	v_mfma_f32_16x16x32_bf16 v[118:121], v[164:167], v[204:207], v[118:121]
	v_mfma_f32_16x16x32_bf16 v[118:121], v[184:187], v[208:211], v[118:121]
	v_mfma_f32_16x16x32_bf16 v[102:105], v[164:167], v[212:215], v[102:105]
	v_mfma_f32_16x16x32_bf16 v[102:105], v[184:187], v[216:219], v[102:105]
	v_mfma_f32_16x16x32_bf16 v[86:89], v[164:167], v[220:223], v[86:89]
	v_mfma_f32_16x16x32_bf16 v[86:89], v[184:187], v[226:229], v[86:89]
	v_mfma_f32_16x16x32_bf16 v[70:73], v[164:167], v[238:241], v[70:73]
	v_mfma_f32_16x16x32_bf16 v[70:73], v[184:187], v[242:245], v[70:73]
	v_mfma_f32_16x16x32_bf16 v[66:69], v[188:191], v[238:241], v[66:69]
	v_mfma_f32_16x16x32_bf16 v[66:69], v[200:203], v[242:245], v[66:69]
	v_mfma_f32_16x16x32_bf16 v[82:85], v[188:191], v[220:223], v[82:85]
	v_mfma_f32_16x16x32_bf16 v[82:85], v[200:203], v[226:229], v[82:85]
	v_mfma_f32_16x16x32_bf16 v[98:101], v[188:191], v[212:215], v[98:101]
	v_mfma_f32_16x16x32_bf16 v[98:101], v[200:203], v[216:219], v[98:101]
	v_mfma_f32_16x16x32_bf16 v[114:117], v[188:191], v[204:207], v[114:117]
	v_mfma_f32_16x16x32_bf16 v[114:117], v[200:203], v[208:211], v[114:117]
	s_setprio 0
	s_barrier
; #define PG8_STAGE(bufoff, gbase, voff) do { _Pragma("unroll") for (int _i = 0; _i < 2; ++_i) \
;         __builtin_amdgcn_global_load_lds((const unsigned*)((const char*)(gbase) + (voff)[_i]), (PG8_LAS unsigned*)(lds + (bufoff) + ldsw + _i * 8192), 16, 0, 0); } while (0)
; #define PG8_LDA(dst, b, h) do { _Pragma("unroll") for (int m = 0; m < 4; ++m) _Pragma("unroll") for (int k = 0; k < 2; ++k) dst[m][k] = *(const PG8_LAS bf16x8*)(lds + PG8_SA(b, h) + aoff + m * 2048 + k * 1024); } while (0)
; #define PG8_MMA(ai, bj, At, Bt) do { __builtin_amdgcn_s_setprio(1); _Pragma("unroll") for (int m = 0; m < 4; ++m) _Pragma("unroll") for (int n = 0; n < 2; ++n) _Pragma("unroll") for (int k = 0; k < 2; ++k) \
;         acc[ai][bj][m][n] = __builtin_amdgcn_mfma_f32_16x16x32_bf16(Bt[n][k], At[m][k], acc[ai][bj][m][n], 0, 0, 0); __builtin_amdgcn_s_setprio(0); } while (0)
; #define PG8_WAIT_V(n) asm volatile("s_waitcnt vmcnt(" #n ")" ::: "memory")
; #define PG8_WAIT_L(n) asm volatile("s_waitcnt lgkmcnt(" #n ")" ::: "memory")
; #define PG8_BAR __builtin_amdgcn_s_barrier()
; #define PG8_SCHED __builtin_amdgcn_sched_barrier(0)
; template <class Epi, class Sched, bool ALIGN_EPI = false, bool SP2 = false>
; __device__ __forceinline__ void gemm_phase(PG8_LAS unsigned char* lds, const Gemm g, const Sched& S, const Epi& E, const int tid) {
;     ...
;         for (int t = 0; t < nt; t += 2) {
;             const bool last = (t == nt - 2);
;             const char* a1 = cA + (size_t)(t + 1) * kstep;
;             const char* a2 = last ? nA : cA + (size_t)(t + 2) * kstep; const char* b2 = last ? nB : cB + (size_t)(t + 2) * kstep;
;             const char* a3 = a2 + kstep; const char* b3 = b2 + kstep;
;     ...
;             PG8_LDA(At, 1, 1); PG8_STAGE(PG8_SB(1, 0), b3, voffB); PG8_STAGE(PG8_SB(1, 1), b3 + hstep, voffB); PG8_STAGE(PG8_SA(1, 0), a3, voffA);
;             PG8_WAIT_V(8); PG8_WAIT_L(0); PG8_BAR; PG8_MMA(1, 0, At, B0); PG8_MMA(1, 1, At, B1); PG8_BAR; PG8_SCHED;
;     ...
;         if constexpr (ALIGN_EPI) { if (wr == 0) PG8_BAR; }
;         if constexpr (!Epi::AFTER_DRAIN) { E(acc, cur, wr, wc, fr, fq); S.done(cur); }
	s_add_i32 s10, s74, s75
	v_lshl_add_u64 v[168:169], v[168:169], 0, s[90:91]
	s_mov_b32 m0, s10
	ds_read_b128 v[204:207], v181 offset:49152
	ds_read_b128 v[208:211], v181 offset:50176
	ds_read_b128 v[212:215], v181 offset:51200
	ds_read_b128 v[216:219], v181 offset:52224
	ds_read_b128 v[220:223], v181 offset:53248
	ds_read_b128 v[226:229], v181 offset:54272
	ds_read_b128 v[238:241], v181 offset:55296
	ds_read_b128 v[242:245], v181 offset:56320
	global_load_lds_dwordx4 v[168:169], off
	v_lshl_add_u64 v[168:169], v[246:247], 0, s[90:91]
	s_add_i32 m0, s10, 0x2000
	s_add_i32 s10, s76, s75
	global_load_lds_dwordx4 v[168:169], off
	v_lshl_add_u64 v[168:169], v[248:249], 0, s[90:91]
	s_mov_b32 m0, s10
	s_nop 0
	global_load_lds_dwordx4 v[168:169], off
	v_lshl_add_u64 v[168:169], v[250:251], 0, s[90:91]
	s_add_i32 m0, s10, 0x2000
	s_nop 0
	global_load_lds_dwordx4 v[168:169], off
	v_lshl_add_u64 v[168:169], v[252:253], 0, s[90:91]
	s_mov_b32 m0, s40
	s_nop 0
	global_load_lds_dwordx4 v[168:169], off
	v_lshl_add_u64 v[168:169], v[194:195], 0, s[90:91]
	s_mov_b32 m0, s41
	s_nop 0
	global_load_lds_dwordx4 v[168:169], off
	s_waitcnt vmcnt(8)
	s_waitcnt lgkmcnt(0)
	s_barrier
	s_setprio 1
	s_waitcnt lgkmcnt(0)
	v_mfma_f32_16x16x32_bf16 v[62:65], v[130:133], v[204:207], v[62:65]
	v_mfma_f32_16x16x32_bf16 v[62:65], v[134:137], v[208:211], v[62:65]
	v_mfma_f32_16x16x32_bf16 v[46:49], v[130:133], v[212:215], v[46:49]
	v_mfma_f32_16x16x32_bf16 v[46:49], v[134:137], v[216:219], v[46:49]
	v_mfma_f32_16x16x32_bf16 v[30:33], v[130:133], v[220:223], v[30:33]
	v_mfma_f32_16x16x32_bf16 v[30:33], v[134:137], v[226:229], v[30:33]
	v_mfma_f32_16x16x32_bf16 v[14:17], v[130:133], v[238:241], v[14:17]
	v_mfma_f32_16x16x32_bf16 v[14:17], v[134:137], v[242:245], v[14:17]
	v_mfma_f32_16x16x32_bf16 v[10:13], v[138:141], v[238:241], v[10:13]
	v_mfma_f32_16x16x32_bf16 v[10:13], v[142:145], v[242:245], v[10:13]
	v_mfma_f32_16x16x32_bf16 v[26:29], v[138:141], v[220:223], v[26:29]
	v_mfma_f32_16x16x32_bf16 v[26:29], v[142:145], v[226:229], v[26:29]
	v_mfma_f32_16x16x32_bf16 v[42:45], v[138:141], v[212:215], v[42:45]
	v_mfma_f32_16x16x32_bf16 v[42:45], v[142:145], v[216:219], v[42:45]
	v_mfma_f32_16x16x32_bf16 v[58:61], v[138:141], v[204:207], v[58:61]
	v_mfma_f32_16x16x32_bf16 v[58:61], v[142:145], v[208:211], v[58:61]
	s_setprio 0
	s_setprio 1
	v_mfma_f32_16x16x32_bf16 v[54:57], v[164:167], v[204:207], v[54:57]
	v_mfma_f32_16x16x32_bf16 v[54:57], v[184:187], v[208:211], v[54:57]
	v_mfma_f32_16x16x32_bf16 v[38:41], v[164:167], v[212:215], v[38:41]
	v_mfma_f32_16x16x32_bf16 v[38:41], v[184:187], v[216:219], v[38:41]
	v_mfma_f32_16x16x32_bf16 v[22:25], v[164:167], v[220:223], v[22:25]
	v_mfma_f32_16x16x32_bf16 v[22:25], v[184:187], v[226:229], v[22:25]
	v_mfma_f32_16x16x32_bf16 v[6:9], v[164:167], v[238:241], v[6:9]
	v_mfma_f32_16x16x32_bf16 v[6:9], v[184:187], v[242:245], v[6:9]
	v_mfma_f32_16x16x32_bf16 v[2:5], v[188:191], v[238:241], v[2:5]
	v_mfma_f32_16x16x32_bf16 v[2:5], v[200:203], v[242:245], v[2:5]
	v_mfma_f32_16x16x32_bf16 v[18:21], v[188:191], v[220:223], v[18:21]
	v_mfma_f32_16x16x32_bf16 v[18:21], v[200:203], v[226:229], v[18:21]
	v_mfma_f32_16x16x32_bf16 v[34:37], v[188:191], v[212:215], v[34:37]
	v_mfma_f32_16x16x32_bf16 v[34:37], v[200:203], v[216:219], v[34:37]
	v_mfma_f32_16x16x32_bf16 v[50:53], v[188:191], v[204:207], v[50:53]
	v_mfma_f32_16x16x32_bf16 v[50:53], v[200:203], v[208:211], v[50:53]
	s_setprio 0
	s_barrier
	s_add_u32 s0, s0, 0x100
	s_addc_u32 s1, s1, 0
	s_add_u32 s12, s12, 0x100
	s_addc_u32 s13, s13, 0
	s_cmp_ge_u32 s69, s84
	s_mov_b32 s10, s69
	s_cbranch_scc0 .LBB0_209
	s_and_b64 vcc, exec, s[22:23]
	s_cbranch_vccz .LBB0_213
	s_barrier
	s_cmp_lt_i32 s3, 3
	s_mov_b64 s[0:1], -1
	s_cbranch_scc0 .LBB0_214
